# non-temporal loads also for the first norm's x rows and the scan2 (1-a,u)/gate streams (each read once)
# baseline (speedup 1.0000x reference)
; __device__ __forceinline__ unsigned cvt_pk_bf16(float lo, float hi) { const bf16x2_t r = __builtin_convertvector((f32x2){lo, hi}, bf16x2_t); return __builtin_bit_cast(unsigned, r); }
; template <bool FINAL>
; __device__ __forceinline__ void norm_phase(const float* X, const float* mod, bf16_t* H, const float* fg, float* OUT, const unsigned long long* acc64 = nullptr, float* modf = nullptr) {
;     ...
;     for (int r = gw; r < MTOK; r += NGW) {
;         const f32x4* xr = (const f32x4*)(X + (size_t)r * DM) + lane;
;         f32x4 v[8]; float ss = 0.f;
; #pragma unroll
;         for (int j = 0; j < 8; ++j) { v[j] = xr[64 * j]; ss += (v[j][0] * v[j][0] + v[j][1] * v[j][1]) + (v[j][2] * v[j][2] + v[j][3] * v[j][3]); }
;         const float rstd = rsqrtf(wave_sum(ss) * (1.0f / DM) + EPS);
;         if (FINAL) {
; #pragma unroll
;             for (int j = 0; j < 8; ++j) { const f32x4 g = *((const f32x4*)fg + lane + 64 * j); *((f32x4*)(OUT + (size_t)r * DM) + lane + 64 * j) = v[j] * rstd * g; }
;         } else {
;             const float* mb = mod + (r >> 12) * 6144; const unsigned long long* mb64 = acc64 + (r >> 12) * 6144;
; #pragma unroll
;             for (int j = 0; j < 8; ++j) { const f32x4 sh = acc64 ? ld_fx4(mb64 + 4 * (lane + 64 * j)) : *((const f32x4*)mb + lane + 64 * j), sc = acc64 ? ld_fx4(mb64 + DM + 4 * (lane + 64 * j)) : *((const f32x4*)(mb + DM) + lane + 64 * j);
;                 const f32x4 o = v[j] * rstd * (sc + 1.0f) + sh; u32x2 w; w.x = cvt_pk_bf16(o[0], o[1]); w.y = cvt_pk_bf16(o[2], o[3]);
;                 *((u32x2*)(H + (size_t)r * DM) + lane + 64 * j) = w; }
.LBB0_121:
	v_ashrrev_i32_e32 v40, 12, v32
	v_mul_i32_i24_e32 v40, 0x1800, v40
	v_ashrrev_i32_e32 v41, 31, v40
	v_add_u32_e32 v32, s4, v32
	v_lshl_add_u64 v[40:41], v[40:41], 3, s[6:7]
	global_load_dwordx4 v[4:7], v[36:37], off offset:-4096 nt
	global_load_dwordx4 v[0:3], v[36:37], off offset:-3072 nt
	global_load_dwordx4 v[8:11], v[36:37], off offset:-2048 nt
	global_load_dwordx4 v[12:15], v[36:37], off nt
	global_load_dwordx4 v[16:19], v[36:37], off offset:1024 nt
	global_load_dwordx4 v[20:23], v[36:37], off offset:-1024 nt
	global_load_dwordx4 v[24:27], v[36:37], off offset:3072 nt
	global_load_dwordx4 v[28:31], v[36:37], off offset:2048 nt
	v_cmp_lt_i32_e32 vcc, s46, v32
	v_lshl_add_u64 v[98:99], v[40:41], 0, v[34:35]
	s_or_b64 s[12:13], vcc, s[12:13]
	global_load_dwordx4 v[82:85], v[98:99], off offset:16
	global_load_dwordx4 v[86:89], v[98:99], off
	v_add_co_u32_e32 v64, vcc, s33, v98
	v_lshl_add_u64 v[100:101], v[98:99], 0, s[14:15]
	s_nop 0
	v_addc_co_u32_e32 v65, vcc, 0, v99, vcc
	global_load_dwordx4 v[90:93], v[64:65], off offset:-4096
	global_load_dwordx4 v[94:97], v[100:101], off offset:16
	v_add_co_u32_e32 v66, vcc, s17, v98
	v_lshl_add_u64 v[72:73], v[98:99], 0, s[2:3]
	s_nop 0
	v_addc_co_u32_e32 v67, vcc, 0, v99, vcc
	v_add_co_u32_e32 v52, vcc, s42, v98
	v_lshl_add_u64 v[74:75], v[98:99], 0, s[18:19]
	s_nop 0
	v_addc_co_u32_e32 v53, vcc, 0, v99, vcc
	v_add_co_u32_e32 v54, vcc, s43, v98
	v_lshl_add_u64 v[70:71], v[98:99], 0, s[20:21]
	s_nop 0
	v_addc_co_u32_e32 v55, vcc, 0, v99, vcc
	v_add_co_u32_e32 v40, vcc, s45, v98
	v_lshl_add_u64 v[68:69], v[98:99], 0, s[22:23]
	s_nop 0
	v_addc_co_u32_e32 v41, vcc, 0, v99, vcc
	v_add_co_u32_e32 v42, vcc, s44, v98
	v_lshl_add_u64 v[62:63], v[98:99], 0, s[24:25]
	s_nop 0
	v_addc_co_u32_e32 v43, vcc, 0, v99, vcc
	v_lshl_add_u64 v[60:61], v[98:99], 0, s[26:27]
	v_lshl_add_u64 v[58:59], v[98:99], 0, s[28:29]
	v_lshl_add_u64 v[56:57], v[98:99], 0, s[30:31]
	v_lshl_add_u64 v[48:49], v[98:99], 0, s[34:35]
	v_lshl_add_u64 v[50:51], v[98:99], 0, s[36:37]
	v_lshl_add_u64 v[46:47], v[98:99], 0, s[38:39]
	v_lshl_add_u64 v[44:45], v[98:99], 0, s[40:41]
	v_lshl_add_u64 v[36:37], v[36:37], 0, s[8:9]
	global_load_dwordx4 v[136:139], v[98:99], off offset:2048
	global_load_dwordx4 v[140:143], v[98:99], off offset:2064
	global_load_dwordx4 v[144:147], v[100:101], off offset:2048
	global_load_dwordx4 v[148:151], v[100:101], off offset:2064
	global_load_dwordx4 v[152:155], v[52:53], off offset:-4096
	global_load_dwordx4 v[156:159], v[72:73], off offset:16
	global_load_dwordx4 v[160:163], v[64:65], off
	global_load_dwordx4 v[164:167], v[74:75], off offset:16
	global_load_dwordx4 v[168:171], v[66:67], off offset:2048
	global_load_dwordx4 v[172:175], v[70:71], off offset:16
	global_load_dwordx4 v[176:179], v[64:65], off offset:2048
	global_load_dwordx4 v[180:183], v[68:69], off offset:16
	global_load_dwordx4 v[184:187], v[52:53], off
	global_load_dwordx4 v[188:191], v[62:63], off offset:16
	global_load_dwordx4 v[196:199], v[40:41], off offset:-4096
	global_load_dwordx4 v[202:205], v[60:61], off offset:16
	global_load_dwordx4 v[206:209], v[52:53], off offset:2048
	global_load_dwordx4 v[210:213], v[58:59], off offset:16
	global_load_dwordx4 v[214:217], v[54:55], off offset:2048
	global_load_dwordx4 v[218:221], v[56:57], off offset:16
	global_load_dwordx4 v[222:225], v[42:43], off
	global_load_dwordx4 v[226:229], v[48:49], off offset:16
	global_load_dwordx4 v[230:233], v[40:41], off
	global_load_dwordx4 v[234:237], v[50:51], off offset:16
	global_load_dwordx4 v[238:241], v[42:43], off offset:2048
	global_load_dwordx4 v[242:245], v[46:47], off offset:16
	global_load_dwordx4 v[246:249], v[40:41], off offset:2048
	global_load_dwordx4 v[250:253], v[44:45], off offset:16
	s_waitcnt vmcnt(39)
	v_mov_b32_e32 v104, v5
	s_waitcnt vmcnt(38)
	v_mov_b32_e32 v105, v1
	v_mov_b32_e32 v108, v7
	v_mov_b32_e32 v109, v3
	v_mov_b32_e32 v102, v4
	v_mov_b32_e32 v103, v0
	v_mov_b32_e32 v106, v6
	v_mov_b32_e32 v107, v2
	s_waitcnt vmcnt(37)
	v_pk_mul_f32 v[110:111], v[10:11], v[10:11]
	v_pk_mul_f32 v[112:113], v[8:9], v[8:9]
	v_pk_mul_f32 v[104:105], v[104:105], v[104:105]
	v_pk_mul_f32 v[108:109], v[108:109], v[108:109]
	v_pk_mov_b32 v[126:127], v[112:113], v[110:111] op_sel:[1,0]
	v_mov_b32_e32 v113, v111
	v_pk_fma_f32 v[102:103], v[102:103], v[102:103], v[104:105]
	v_pk_fma_f32 v[104:105], v[106:107], v[106:107], v[108:109]
	s_waitcnt vmcnt(35)
	v_pk_mul_f32 v[114:115], v[18:19], v[18:19]
	v_pk_mul_f32 v[116:117], v[16:17], v[16:17]
	s_waitcnt vmcnt(34)
	v_mul_f32_e32 v118, v21, v21
	v_mul_f32_e32 v120, v23, v23
	v_pk_add_f32 v[106:107], v[126:127], v[112:113]
	v_pk_add_f32 v[102:103], v[102:103], v[104:105]
	v_mul_f32_e32 v125, v12, v12
	v_mul_f32_e32 v128, v13, v13
	v_mul_f32_e32 v129, v14, v14
	v_mul_f32_e32 v130, v15, v15
	v_pk_mov_b32 v[110:111], v[116:117], v[114:115] op_sel:[1,0]
	v_mov_b32_e32 v117, v115
	v_pk_fma_f32 v[114:115], v[20:21], v[20:21], v[118:119] op_sel_hi:[1,1,0]
	v_pk_fma_f32 v[118:119], v[22:23], v[22:23], v[120:121] op_sel_hi:[1,1,0]
	v_pk_add_f32 v[104:105], v[106:107], v[106:107] op_sel:[0,1] op_sel_hi:[1,0]
	v_pk_add_f32 v[102:103], v[102:103], v[102:103] op_sel:[0,1] op_sel_hi:[1,0]
	s_waitcnt vmcnt(32)
	v_mul_f32_e32 v122, v29, v29
	v_mul_f32_e32 v124, v31, v31
	v_mov_b32_e32 v115, v129
	v_mov_b32_e32 v119, v130
	v_mov_b32_e32 v105, v128
	v_mov_b32_e32 v103, v125
	v_mul_f32_e32 v133, v26, v26
	v_mul_f32_e32 v134, v27, v27
	v_pk_fma_f32 v[120:121], v[28:29], v[28:29], v[122:123] op_sel_hi:[1,1,0]
	v_pk_fma_f32 v[122:123], v[30:31], v[30:31], v[124:125] op_sel_hi:[1,1,0]
	v_pk_add_f32 v[108:109], v[110:111], v[116:117]
	v_pk_add_f32 v[106:107], v[114:115], v[118:119]
	s_waitcnt vmcnt(30)
; __device__ __forceinline__ unsigned cvt_pk_bf16(float lo, float hi) { const bf16x2_t r = __builtin_convertvector((f32x2){lo, hi}, bf16x2_t); return __builtin_bit_cast(unsigned, r); }
; __device__ __forceinline__ float wave_sum(float v) {
; #pragma unroll
;     for (int o = 1; o < 64; o <<= 1) v += __shfl_xor(v, o);
;     return v;
; template <bool FINAL>
; __device__ __forceinline__ void norm_phase(const float* X, const float* mod, bf16_t* H, const float* fg, float* OUT, const unsigned long long* acc64 = nullptr, float* modf = nullptr) {
;     ...
;         for (int j = 0; j < 8; ++j) { v[j] = xr[64 * j]; ss += (v[j][0] * v[j][0] + v[j][1] * v[j][1]) + (v[j][2] * v[j][2] + v[j][3] * v[j][3]); }
;         const float rstd = rsqrtf(wave_sum(ss) * (1.0f / DM) + EPS);
;         if (FINAL) {
; #pragma unroll
;             for (int j = 0; j < 8; ++j) { const f32x4 g = *((const f32x4*)fg + lane + 64 * j); *((f32x4*)(OUT + (size_t)r * DM) + lane + 64 * j) = v[j] * rstd * g; }
;         } else {
;             const float* mb = mod + (r >> 12) * 6144; const unsigned long long* mb64 = acc64 + (r >> 12) * 6144;
; #pragma unroll
;             for (int j = 0; j < 8; ++j) { const f32x4 sh = acc64 ? ld_fx4(mb64 + 4 * (lane + 64 * j)) : *((const f32x4*)mb + lane + 64 * j), sc = acc64 ? ld_fx4(mb64 + DM + 4 * (lane + 64 * j)) : *((const f32x4*)(mb + DM) + lane + 64 * j);
;                 const f32x4 o = v[j] * rstd * (sc + 1.0f) + sh; u32x2 w; w.x = cvt_pk_bf16(o[0], o[1]); w.y = cvt_pk_bf16(o[2], o[3]);
;                 *((u32x2*)(H + (size_t)r * DM) + lane + 64 * j) = w; }
	v_xor_b32_e32 v112, v86, v87
	v_xor_b32_e32 v114, v88, v89
	v_xor_b32_e32 v116, v82, v83
	v_xor_b32_e32 v118, v84, v85
	v_pk_add_f32 v[102:103], v[102:103], v[104:105]
	v_mov_b32_e32 v121, v133
	v_mov_b32_e32 v123, v134
	v_ffbh_i32_e32 v113, v87
	v_ffbh_i32_e32 v115, v89
	v_ffbh_i32_e32 v117, v83
	v_ffbh_i32_e32 v119, v85
	v_ashrrev_i32_e32 v104, 31, v112
	v_ashrrev_i32_e32 v112, 31, v114
	v_ashrrev_i32_e32 v114, 31, v116
	v_ashrrev_i32_e32 v116, 31, v118
	s_waitcnt vmcnt(29)
	v_xor_b32_e32 v118, v90, v91
	v_pk_add_f32 v[102:103], v[102:103], v[106:107]
	v_mul_f32_e32 v131, v24, v24
	v_mul_f32_e32 v132, v25, v25
	v_pk_add_f32 v[108:109], v[108:109], v[108:109] op_sel:[0,1] op_sel_hi:[1,0]
	v_pk_add_f32 v[110:111], v[120:121], v[122:123]
	v_add_u32_e32 v105, -1, v113
	v_add_u32_e32 v113, -1, v115
	v_add_u32_e32 v115, -1, v117
	v_add_u32_e32 v117, -1, v119
	v_ffbh_i32_e32 v119, v91
	v_xor_b32_e32 v120, v92, v93
	v_add_u32_e32 v104, 32, v104
	v_add_u32_e32 v106, 32, v112
	v_add_u32_e32 v107, 32, v114
	v_add_u32_e32 v112, 32, v116
	v_ashrrev_i32_e32 v114, 31, v118
	v_pk_add_f32 v[102:103], v[102:103], v[102:103] op_sel:[0,1] op_sel_hi:[1,0]
	v_mov_b32_e32 v109, v132
	v_ffbh_i32_e32 v121, v93
	v_add_u32_e32 v116, -1, v119
	v_ashrrev_i32_e32 v118, 31, v120
	v_min_u32_e32 v104, v105, v104
	v_min_u32_e32 v105, v113, v106
	v_min_u32_e32 v106, v115, v107
	v_min_u32_e32 v107, v117, v112
	v_add_u32_e32 v112, 32, v114
	v_mov_b32_e32 v103, v131
	v_add_u32_e32 v119, -1, v121
	v_add_u32_e32 v113, 32, v118
	v_lshlrev_b64 v[82:83], v106, v[82:83]
	v_lshlrev_b64 v[84:85], v107, v[84:85]
	v_min_u32_e32 v112, v116, v112
	v_pk_add_f32 v[102:103], v[102:103], v[108:109]
	v_min_u32_e32 v113, v119, v113
	v_min_u32_e32 v82, 1, v82
	v_min_u32_e32 v84, 1, v84
	v_lshlrev_b64 v[90:91], v112, v[90:91]
	v_pk_add_f32 v[102:103], v[102:103], v[110:111]
	v_lshlrev_b64 v[92:93], v113, v[92:93]
	v_or_b32_e32 v82, v83, v82
	v_or_b32_e32 v83, v85, v84
	v_min_u32_e32 v84, 1, v90
	v_add_f32_e32 v90, v102, v103
	v_min_u32_e32 v85, 1, v92
	v_cvt_f32_i32_e32 v92, v82
	v_or_b32_e32 v82, v91, v84
	ds_bpermute_b32 v91, v76, v90
	s_waitcnt vmcnt(28)
	v_xor_b32_e32 v122, v94, v95
	v_xor_b32_e32 v124, v96, v97
	v_ffbh_i32_e32 v123, v95
	v_ffbh_i32_e32 v125, v97
	s_waitcnt lgkmcnt(0)
	v_add_f32_e32 v90, v90, v91
	ds_bpermute_b32 v91, v77, v90
	v_ashrrev_i32_e32 v120, 31, v122
	v_ashrrev_i32_e32 v122, 31, v124
	v_add_u32_e32 v121, -1, v123
	v_add_u32_e32 v123, -1, v125
	s_waitcnt lgkmcnt(0)
	v_add_f32_e32 v90, v90, v91
	ds_bpermute_b32 v91, v78, v90
	v_add_u32_e32 v114, 32, v120
	v_add_u32_e32 v115, 32, v122
	v_lshlrev_b64 v[86:87], v104, v[86:87]
	v_lshlrev_b64 v[88:89], v105, v[88:89]
	s_waitcnt lgkmcnt(0)
	v_add_f32_e32 v90, v90, v91
	ds_bpermute_b32 v91, v79, v90
	v_min_u32_e32 v114, v121, v114
	v_min_u32_e32 v115, v123, v115
	v_min_u32_e32 v86, 1, v86
	v_min_u32_e32 v88, 1, v88
	s_waitcnt lgkmcnt(0)
	v_add_f32_e32 v90, v90, v91
	ds_bpermute_b32 v91, v80, v90
	v_lshlrev_b64 v[94:95], v114, v[94:95]
	v_lshlrev_b64 v[96:97], v115, v[96:97]
	v_or_b32_e32 v86, v87, v86
	v_or_b32_e32 v87, v89, v88
	s_waitcnt lgkmcnt(0)
	v_add_f32_e32 v90, v90, v91
	ds_bpermute_b32 v91, v81, v90
	v_min_u32_e32 v88, 1, v94
	v_min_u32_e32 v89, 1, v96
	v_cvt_f32_i32_e32 v94, v83
	v_or_b32_e32 v83, v93, v85
	s_waitcnt lgkmcnt(0)
	v_add_f32_e32 v90, v90, v91
	v_fmamk_f32 v90, v90, 0x3a000000, v33
	v_mul_f32_e32 v91, 0x4b800000, v90
	v_cmp_gt_f32_e32 vcc, s5, v90
	v_or_b32_e32 v84, v95, v88
	v_or_b32_e32 v85, v97, v89
	v_cndmask_b32_e32 v90, v90, v91, vcc
	v_rsq_f32_e32 v90, v90
	v_cvt_f32_i32_e32 v86, v86
	v_cvt_f32_i32_e32 v87, v87
	v_cvt_f32_i32_e32 v88, v82
	v_cvt_f32_i32_e32 v89, v83
	v_cvt_f32_i32_e32 v93, v84
	v_cvt_f32_i32_e32 v95, v85
	v_sub_u32_e32 v104, 32, v104
	v_sub_u32_e32 v105, 32, v105
	v_sub_u32_e32 v108, 32, v112
	v_sub_u32_e32 v109, 32, v113
	v_sub_u32_e32 v112, 32, v114
	v_sub_u32_e32 v113, 32, v115
	v_mul_f32_e32 v91, 0x45800000, v90
	v_sub_u32_e32 v106, 32, v106
	v_sub_u32_e32 v107, 32, v107
	v_ldexp_f32 v82, v86, v104
	v_ldexp_f32 v83, v87, v105
	v_ldexp_f32 v86, v88, v108
	v_ldexp_f32 v87, v89, v109
	v_ldexp_f32 v88, v93, v112
	v_ldexp_f32 v89, v95, v113
	v_cndmask_b32_e32 v90, v90, v91, vcc
	v_ldexp_f32 v84, v92, v106
	v_ldexp_f32 v85, v94, v107
	v_pk_fma_f32 v[86:87], v[86:87], s[16:17], 1.0 op_sel_hi:[1,0,0]
	v_pk_fma_f32 v[88:89], v[88:89], s[16:17], 1.0 op_sel_hi:[1,0,0]
	v_pk_mul_f32 v[92:93], v[6:7], v[90:91] op_sel_hi:[1,0]
	v_pk_mul_f32 v[94:95], v[4:5], v[90:91] op_sel_hi:[1,0]
	v_pk_mul_f32 v[104:105], v[10:11], v[90:91] op_sel_hi:[1,0]
	v_pk_mul_f32 v[106:107], v[8:9], v[90:91] op_sel_hi:[1,0]
	v_pk_mul_f32 v[8:9], v[18:19], v[90:91] op_sel_hi:[1,0]
	v_pk_mul_f32 v[10:11], v[16:17], v[90:91] op_sel_hi:[1,0]
	v_pk_mul_f32 v[16:17], v[86:87], v[94:95]
	v_pk_mul_f32 v[18:19], v[88:89], v[92:93]
	v_pk_fma_f32 v[16:17], v[82:83], s[16:17], v[16:17] op_sel_hi:[1,0,1]
	v_pk_fma_f32 v[18:19], v[84:85], s[16:17], v[18:19] op_sel_hi:[1,0,1]
	v_cvt_pk_bf16_f32 v16, v16, v17
	v_cvt_pk_bf16_f32 v17, v18, v19
	global_store_dwordx2 v[38:39], v[16:17], off
	v_pk_mul_f32 v[96:97], v[2:3], v[90:91] op_sel_hi:[1,0]
	v_pk_mul_f32 v[102:103], v[0:1], v[90:91] op_sel_hi:[1,0]
	v_pk_mul_f32 v[4:5], v[30:31], v[90:91] op_sel_hi:[1,0]
	v_pk_mul_f32 v[6:7], v[28:29], v[90:91] op_sel_hi:[1,0]
	v_pk_mul_f32 v[0:1], v[26:27], v[90:91] op_sel_hi:[1,0]
	v_pk_mul_f32 v[2:3], v[24:25], v[90:91] op_sel_hi:[1,0]
	s_waitcnt vmcnt(25)
; __device__ __forceinline__ unsigned cvt_pk_bf16(float lo, float hi) { const bf16x2_t r = __builtin_convertvector((f32x2){lo, hi}, bf16x2_t); return __builtin_bit_cast(unsigned, r); }
; __device__ __forceinline__ f32x4 ld_fx4(const unsigned long long* p) {
;     const long long a = (long long)p[0], b = (long long)p[1], c = (long long)p[2], d = (long long)p[3];
;     return (f32x4){(float)a, (float)b, (float)c, (float)d} * 9.094947017729282e-13f;
; }
; template <bool FINAL>
; __device__ __forceinline__ void norm_phase(const float* X, const float* mod, bf16_t* H, const float* fg, float* OUT, const unsigned long long* acc64 = nullptr, float* modf = nullptr) {
;     ...
;             const float* mb = mod + (r >> 12) * 6144; const unsigned long long* mb64 = acc64 + (r >> 12) * 6144;
; #pragma unroll
;             for (int j = 0; j < 8; ++j) { const f32x4 sh = acc64 ? ld_fx4(mb64 + 4 * (lane + 64 * j)) : *((const f32x4*)mb + lane + 64 * j), sc = acc64 ? ld_fx4(mb64 + DM + 4 * (lane + 64 * j)) : *((const f32x4*)(mb + DM) + lane + 64 * j);
;                 const f32x4 o = v[j] * rstd * (sc + 1.0f) + sh; u32x2 w; w.x = cvt_pk_bf16(o[0], o[1]); w.y = cvt_pk_bf16(o[2], o[3]);
;                 *((u32x2*)(H + (size_t)r * DM) + lane + 64 * j) = w; }
	v_mov_b32_e32 v16, v136
	v_mov_b32_e32 v17, v137
	v_mov_b32_e32 v18, v138
	v_mov_b32_e32 v19, v139
	v_mov_b32_e32 v24, v140
	v_mov_b32_e32 v25, v141
	v_mov_b32_e32 v26, v142
	v_mov_b32_e32 v27, v143
	v_mov_b32_e32 v28, v144
	v_mov_b32_e32 v29, v145
	v_mov_b32_e32 v30, v146
	v_mov_b32_e32 v31, v147
	v_mov_b32_e32 v82, v148
	v_mov_b32_e32 v83, v149
	v_mov_b32_e32 v84, v150
	v_mov_b32_e32 v85, v151
	v_pk_mul_f32 v[22:23], v[22:23], v[90:91] op_sel_hi:[1,0]
	v_pk_mul_f32 v[20:21], v[20:21], v[90:91] op_sel_hi:[1,0]
	v_pk_mul_f32 v[14:15], v[14:15], v[90:91] op_sel_hi:[1,0]
	v_pk_mul_f32 v[12:13], v[12:13], v[90:91] op_sel_hi:[1,0]
	v_xor_b32_e32 v86, v16, v17
	v_xor_b32_e32 v88, v18, v19
	v_xor_b32_e32 v90, v24, v25
	v_xor_b32_e32 v92, v26, v27
	v_xor_b32_e32 v94, v28, v29
	v_xor_b32_e32 v98, v30, v31
	v_xor_b32_e32 v100, v82, v83
	v_xor_b32_e32 v108, v84, v85
	v_ffbh_i32_e32 v87, v17
	v_ffbh_i32_e32 v89, v19
	v_ffbh_i32_e32 v91, v25
	v_ffbh_i32_e32 v93, v27
	v_ffbh_i32_e32 v95, v29
	v_ffbh_i32_e32 v99, v31
	v_ffbh_i32_e32 v101, v83
	v_ffbh_i32_e32 v109, v85
	v_ashrrev_i32_e32 v86, 31, v86
	v_ashrrev_i32_e32 v88, 31, v88
	v_ashrrev_i32_e32 v90, 31, v90
	v_ashrrev_i32_e32 v92, 31, v92
	v_ashrrev_i32_e32 v94, 31, v94
	v_ashrrev_i32_e32 v98, 31, v98
	v_ashrrev_i32_e32 v100, 31, v100
	v_ashrrev_i32_e32 v108, 31, v108
	v_add_u32_e32 v87, -1, v87
	v_add_u32_e32 v89, -1, v89
	v_add_u32_e32 v91, -1, v91
	v_add_u32_e32 v93, -1, v93
	v_add_u32_e32 v95, -1, v95
	v_add_u32_e32 v99, -1, v99
	v_add_u32_e32 v101, -1, v101
	v_add_u32_e32 v109, -1, v109
	v_add_u32_e32 v86, 32, v86
	v_add_u32_e32 v88, 32, v88
	v_add_u32_e32 v90, 32, v90
	v_add_u32_e32 v92, 32, v92
	v_add_u32_e32 v94, 32, v94
	v_add_u32_e32 v98, 32, v98
	v_add_u32_e32 v100, 32, v100
	v_add_u32_e32 v108, 32, v108
	v_min_u32_e32 v86, v87, v86
	v_min_u32_e32 v87, v89, v88
	v_min_u32_e32 v88, v91, v90
	v_min_u32_e32 v89, v93, v92
	v_min_u32_e32 v90, v95, v94
	v_min_u32_e32 v91, v99, v98
	v_min_u32_e32 v92, v101, v100
	v_min_u32_e32 v93, v109, v108
	v_lshlrev_b64 v[16:17], v86, v[16:17]
	v_lshlrev_b64 v[18:19], v87, v[18:19]
	v_lshlrev_b64 v[24:25], v88, v[24:25]
	v_lshlrev_b64 v[26:27], v89, v[26:27]
	v_lshlrev_b64 v[28:29], v90, v[28:29]
	v_lshlrev_b64 v[30:31], v91, v[30:31]
	v_lshlrev_b64 v[82:83], v92, v[82:83]
	v_lshlrev_b64 v[84:85], v93, v[84:85]
	v_min_u32_e32 v16, 1, v16
	v_min_u32_e32 v18, 1, v18
	v_min_u32_e32 v24, 1, v24
	v_min_u32_e32 v26, 1, v26
	v_min_u32_e32 v28, 1, v28
	v_min_u32_e32 v30, 1, v30
	v_min_u32_e32 v82, 1, v82
	v_min_u32_e32 v84, 1, v84
	v_or_b32_e32 v16, v17, v16
	v_or_b32_e32 v17, v19, v18
	v_or_b32_e32 v18, v25, v24
	v_or_b32_e32 v19, v27, v26
	v_or_b32_e32 v24, v29, v28
	v_or_b32_e32 v25, v31, v30
	v_or_b32_e32 v26, v83, v82
	v_or_b32_e32 v27, v85, v84
	v_cvt_f32_i32_e32 v24, v24
	v_cvt_f32_i32_e32 v25, v25
	v_cvt_f32_i32_e32 v26, v26
	v_cvt_f32_i32_e32 v27, v27
	v_cvt_f32_i32_e32 v16, v16
	v_cvt_f32_i32_e32 v17, v17
	v_cvt_f32_i32_e32 v18, v18
	v_cvt_f32_i32_e32 v19, v19
	v_sub_u32_e32 v90, 32, v90
	v_sub_u32_e32 v91, 32, v91
	v_sub_u32_e32 v92, 32, v92
	v_sub_u32_e32 v93, 32, v93
	v_ldexp_f32 v24, v24, v90
	v_ldexp_f32 v25, v25, v91
	v_ldexp_f32 v26, v26, v92
	v_ldexp_f32 v27, v27, v93
	v_sub_u32_e32 v86, 32, v86
	v_sub_u32_e32 v87, 32, v87
	v_sub_u32_e32 v88, 32, v88
	v_sub_u32_e32 v89, 32, v89
	v_pk_fma_f32 v[26:27], v[26:27], s[16:17], 1.0 op_sel_hi:[1,0,0]
	v_pk_fma_f32 v[24:25], v[24:25], s[16:17], 1.0 op_sel_hi:[1,0,0]
	v_ldexp_f32 v16, v16, v86
	v_ldexp_f32 v17, v17, v87
	v_ldexp_f32 v18, v18, v88
	v_ldexp_f32 v19, v19, v89
	v_pk_mul_f32 v[24:25], v[102:103], v[24:25]
	v_pk_mul_f32 v[26:27], v[96:97], v[26:27]
	v_pk_fma_f32 v[16:17], v[16:17], s[16:17], v[24:25] op_sel_hi:[1,0,1]
	v_pk_fma_f32 v[18:19], v[18:19], s[16:17], v[26:27] op_sel_hi:[1,0,1]
	v_cvt_pk_bf16_f32 v16, v16, v17
	v_cvt_pk_bf16_f32 v17, v18, v19
	global_store_dwordx2 v[38:39], v[16:17], off offset:512
	s_waitcnt vmcnt(22)
	v_mov_b32_e32 v16, v152
	v_mov_b32_e32 v17, v153
	v_mov_b32_e32 v18, v154
	v_mov_b32_e32 v19, v155
	v_mov_b32_e32 v24, v156
	v_mov_b32_e32 v25, v157
	v_mov_b32_e32 v26, v158
	v_mov_b32_e32 v27, v159
	v_mov_b32_e32 v28, v160
	v_mov_b32_e32 v29, v161
	v_mov_b32_e32 v30, v162
	v_mov_b32_e32 v31, v163
	v_mov_b32_e32 v72, v164
	v_mov_b32_e32 v73, v165
	v_mov_b32_e32 v74, v166
	v_mov_b32_e32 v75, v167
	v_xor_b32_e32 v82, v16, v17
	v_xor_b32_e32 v84, v18, v19
	v_xor_b32_e32 v86, v24, v25
	v_xor_b32_e32 v88, v26, v27
	v_xor_b32_e32 v90, v28, v29
	v_xor_b32_e32 v92, v30, v31
	v_xor_b32_e32 v94, v72, v73
	v_xor_b32_e32 v96, v74, v75
	v_ffbh_i32_e32 v83, v17
	v_ffbh_i32_e32 v85, v19
	v_ffbh_i32_e32 v87, v25
	v_ffbh_i32_e32 v89, v27
	v_ffbh_i32_e32 v91, v29
	v_ffbh_i32_e32 v93, v31
	v_ffbh_i32_e32 v95, v73
	v_ffbh_i32_e32 v97, v75
	v_ashrrev_i32_e32 v82, 31, v82
	v_ashrrev_i32_e32 v84, 31, v84
	v_ashrrev_i32_e32 v86, 31, v86
	v_ashrrev_i32_e32 v88, 31, v88
	v_ashrrev_i32_e32 v90, 31, v90
	v_ashrrev_i32_e32 v92, 31, v92
	v_ashrrev_i32_e32 v94, 31, v94
	v_ashrrev_i32_e32 v96, 31, v96
	v_add_u32_e32 v83, -1, v83
	v_add_u32_e32 v85, -1, v85
	v_add_u32_e32 v87, -1, v87
	v_add_u32_e32 v89, -1, v89
	v_add_u32_e32 v91, -1, v91
	v_add_u32_e32 v93, -1, v93
	v_add_u32_e32 v95, -1, v95
	v_add_u32_e32 v97, -1, v97
	v_add_u32_e32 v82, 32, v82
	v_add_u32_e32 v84, 32, v84
	v_add_u32_e32 v86, 32, v86
	v_add_u32_e32 v88, 32, v88
	v_add_u32_e32 v90, 32, v90
	v_add_u32_e32 v92, 32, v92
	v_add_u32_e32 v94, 32, v94
	v_add_u32_e32 v96, 32, v96
	v_min_u32_e32 v82, v83, v82
	v_min_u32_e32 v83, v85, v84
	v_min_u32_e32 v84, v87, v86
	v_min_u32_e32 v85, v89, v88
	v_min_u32_e32 v86, v91, v90
; __device__ __forceinline__ unsigned cvt_pk_bf16(float lo, float hi) { const bf16x2_t r = __builtin_convertvector((f32x2){lo, hi}, bf16x2_t); return __builtin_bit_cast(unsigned, r); }
; __device__ __forceinline__ f32x4 ld_fx4(const unsigned long long* p) {
;     const long long a = (long long)p[0], b = (long long)p[1], c = (long long)p[2], d = (long long)p[3];
;     return (f32x4){(float)a, (float)b, (float)c, (float)d} * 9.094947017729282e-13f;
; }
; template <bool FINAL>
; __device__ __forceinline__ void norm_phase(const float* X, const float* mod, bf16_t* H, const float* fg, float* OUT, const unsigned long long* acc64 = nullptr, float* modf = nullptr) {
;     ...
;             const float* mb = mod + (r >> 12) * 6144; const unsigned long long* mb64 = acc64 + (r >> 12) * 6144;
; #pragma unroll
;             for (int j = 0; j < 8; ++j) { const f32x4 sh = acc64 ? ld_fx4(mb64 + 4 * (lane + 64 * j)) : *((const f32x4*)mb + lane + 64 * j), sc = acc64 ? ld_fx4(mb64 + DM + 4 * (lane + 64 * j)) : *((const f32x4*)(mb + DM) + lane + 64 * j);
;                 const f32x4 o = v[j] * rstd * (sc + 1.0f) + sh; u32x2 w; w.x = cvt_pk_bf16(o[0], o[1]); w.y = cvt_pk_bf16(o[2], o[3]);
;                 *((u32x2*)(H + (size_t)r * DM) + lane + 64 * j) = w; }
	v_min_u32_e32 v87, v93, v92
	v_min_u32_e32 v88, v95, v94
	v_min_u32_e32 v89, v97, v96
	v_lshlrev_b64 v[16:17], v82, v[16:17]
	v_lshlrev_b64 v[18:19], v83, v[18:19]
	v_lshlrev_b64 v[24:25], v84, v[24:25]
	v_lshlrev_b64 v[26:27], v85, v[26:27]
	v_lshlrev_b64 v[28:29], v86, v[28:29]
	v_lshlrev_b64 v[30:31], v87, v[30:31]
	v_lshlrev_b64 v[72:73], v88, v[72:73]
	v_lshlrev_b64 v[74:75], v89, v[74:75]
	v_min_u32_e32 v16, 1, v16
	v_min_u32_e32 v18, 1, v18
	v_min_u32_e32 v24, 1, v24
	v_min_u32_e32 v26, 1, v26
	v_min_u32_e32 v28, 1, v28
	v_min_u32_e32 v30, 1, v30
	v_min_u32_e32 v72, 1, v72
	v_min_u32_e32 v74, 1, v74
	v_or_b32_e32 v16, v17, v16
	v_or_b32_e32 v17, v19, v18
	v_or_b32_e32 v18, v25, v24
	v_or_b32_e32 v19, v27, v26
	v_or_b32_e32 v24, v29, v28
	v_or_b32_e32 v25, v31, v30
	v_or_b32_e32 v26, v73, v72
	v_or_b32_e32 v27, v75, v74
	v_cvt_f32_i32_e32 v24, v24
	v_cvt_f32_i32_e32 v25, v25
	v_cvt_f32_i32_e32 v26, v26
	v_cvt_f32_i32_e32 v27, v27
	v_cvt_f32_i32_e32 v16, v16
	v_cvt_f32_i32_e32 v17, v17
	v_cvt_f32_i32_e32 v18, v18
	v_cvt_f32_i32_e32 v19, v19
	v_sub_u32_e32 v86, 32, v86
	v_sub_u32_e32 v87, 32, v87
	v_sub_u32_e32 v88, 32, v88
	v_sub_u32_e32 v89, 32, v89
	v_ldexp_f32 v24, v24, v86
	v_ldexp_f32 v25, v25, v87
	v_ldexp_f32 v26, v26, v88
	v_ldexp_f32 v27, v27, v89
	v_sub_u32_e32 v82, 32, v82
	v_sub_u32_e32 v83, 32, v83
	v_sub_u32_e32 v84, 32, v84
	v_sub_u32_e32 v85, 32, v85
	v_pk_fma_f32 v[24:25], v[24:25], s[16:17], 1.0 op_sel_hi:[1,0,0]
	v_pk_fma_f32 v[26:27], v[26:27], s[16:17], 1.0 op_sel_hi:[1,0,0]
	v_ldexp_f32 v16, v16, v82
	v_ldexp_f32 v17, v17, v83
	v_ldexp_f32 v18, v18, v84
	v_ldexp_f32 v19, v19, v85
	v_pk_mul_f32 v[24:25], v[106:107], v[24:25]
	v_pk_mul_f32 v[26:27], v[104:105], v[26:27]
	v_pk_fma_f32 v[16:17], v[16:17], s[16:17], v[24:25] op_sel_hi:[1,0,1]
	v_pk_fma_f32 v[18:19], v[18:19], s[16:17], v[26:27] op_sel_hi:[1,0,1]
	v_cvt_pk_bf16_f32 v16, v16, v17
	v_cvt_pk_bf16_f32 v17, v18, v19
	global_store_dwordx2 v[38:39], v[16:17], off offset:1024
	s_waitcnt vmcnt(19)
	v_mov_b32_e32 v16, v168
	v_mov_b32_e32 v17, v169
	v_mov_b32_e32 v18, v170
	v_mov_b32_e32 v19, v171
	v_mov_b32_e32 v24, v172
	v_mov_b32_e32 v25, v173
	v_mov_b32_e32 v26, v174
	v_mov_b32_e32 v27, v175
	v_mov_b32_e32 v28, v176
	v_mov_b32_e32 v29, v177
	v_mov_b32_e32 v30, v178
	v_mov_b32_e32 v31, v179
	v_mov_b32_e32 v64, v180
	v_mov_b32_e32 v65, v181
	v_mov_b32_e32 v66, v182
	v_mov_b32_e32 v67, v183
	v_xor_b32_e32 v68, v16, v17
	v_xor_b32_e32 v70, v18, v19
	v_xor_b32_e32 v72, v24, v25
	v_xor_b32_e32 v74, v26, v27
	v_xor_b32_e32 v82, v28, v29
	v_xor_b32_e32 v84, v30, v31
	v_xor_b32_e32 v86, v64, v65
	v_xor_b32_e32 v88, v66, v67
	v_ffbh_i32_e32 v69, v17
	v_ffbh_i32_e32 v71, v19
	v_ffbh_i32_e32 v73, v25
	v_ffbh_i32_e32 v75, v27
	v_ffbh_i32_e32 v83, v29
	v_ffbh_i32_e32 v85, v31
	v_ffbh_i32_e32 v87, v65
	v_ffbh_i32_e32 v89, v67
	v_ashrrev_i32_e32 v68, 31, v68
	v_ashrrev_i32_e32 v70, 31, v70
	v_ashrrev_i32_e32 v72, 31, v72
	v_ashrrev_i32_e32 v74, 31, v74
	v_ashrrev_i32_e32 v82, 31, v82
	v_ashrrev_i32_e32 v84, 31, v84
	v_ashrrev_i32_e32 v86, 31, v86
	v_ashrrev_i32_e32 v88, 31, v88
	v_add_u32_e32 v69, -1, v69
	v_add_u32_e32 v71, -1, v71
	v_add_u32_e32 v73, -1, v73
	v_add_u32_e32 v75, -1, v75
	v_add_u32_e32 v83, -1, v83
	v_add_u32_e32 v85, -1, v85
	v_add_u32_e32 v87, -1, v87
	v_add_u32_e32 v89, -1, v89
	v_add_u32_e32 v68, 32, v68
	v_add_u32_e32 v70, 32, v70
	v_add_u32_e32 v72, 32, v72
	v_add_u32_e32 v74, 32, v74
	v_add_u32_e32 v82, 32, v82
	v_add_u32_e32 v84, 32, v84
	v_add_u32_e32 v86, 32, v86
	v_add_u32_e32 v88, 32, v88
	v_min_u32_e32 v68, v69, v68
	v_min_u32_e32 v69, v71, v70
	v_min_u32_e32 v70, v73, v72
	v_min_u32_e32 v71, v75, v74
	v_min_u32_e32 v72, v83, v82
	v_min_u32_e32 v73, v85, v84
	v_min_u32_e32 v74, v87, v86
	v_min_u32_e32 v75, v89, v88
	v_lshlrev_b64 v[16:17], v68, v[16:17]
	v_lshlrev_b64 v[18:19], v69, v[18:19]
	v_lshlrev_b64 v[24:25], v70, v[24:25]
	v_lshlrev_b64 v[26:27], v71, v[26:27]
	v_lshlrev_b64 v[28:29], v72, v[28:29]
	v_lshlrev_b64 v[30:31], v73, v[30:31]
	v_lshlrev_b64 v[64:65], v74, v[64:65]
	v_lshlrev_b64 v[66:67], v75, v[66:67]
	v_min_u32_e32 v16, 1, v16
	v_min_u32_e32 v18, 1, v18
	v_min_u32_e32 v24, 1, v24
	v_min_u32_e32 v26, 1, v26
	v_min_u32_e32 v28, 1, v28
	v_min_u32_e32 v30, 1, v30
	v_min_u32_e32 v64, 1, v64
	v_min_u32_e32 v66, 1, v66
	v_or_b32_e32 v16, v17, v16
	v_or_b32_e32 v17, v19, v18
	v_or_b32_e32 v18, v25, v24
	v_or_b32_e32 v19, v27, v26
	v_or_b32_e32 v24, v29, v28
	v_or_b32_e32 v25, v31, v30
	v_or_b32_e32 v26, v65, v64
	v_or_b32_e32 v27, v67, v66
	v_cvt_f32_i32_e32 v24, v24
	v_cvt_f32_i32_e32 v25, v25
	v_cvt_f32_i32_e32 v26, v26
	v_cvt_f32_i32_e32 v27, v27
	v_cvt_f32_i32_e32 v16, v16
	v_cvt_f32_i32_e32 v17, v17
	v_cvt_f32_i32_e32 v18, v18
	v_cvt_f32_i32_e32 v19, v19
	v_sub_u32_e32 v72, 32, v72
	v_sub_u32_e32 v73, 32, v73
	v_sub_u32_e32 v74, 32, v74
	v_sub_u32_e32 v75, 32, v75
	v_ldexp_f32 v24, v24, v72
	v_ldexp_f32 v25, v25, v73
	v_ldexp_f32 v26, v26, v74
	v_ldexp_f32 v27, v27, v75
	v_sub_u32_e32 v68, 32, v68
	v_sub_u32_e32 v69, 32, v69
	v_sub_u32_e32 v70, 32, v70
	v_sub_u32_e32 v71, 32, v71
	v_pk_fma_f32 v[24:25], v[24:25], s[16:17], 1.0 op_sel_hi:[1,0,0]
	v_pk_fma_f32 v[26:27], v[26:27], s[16:17], 1.0 op_sel_hi:[1,0,0]
	v_ldexp_f32 v16, v16, v68
	v_ldexp_f32 v17, v17, v69
	v_ldexp_f32 v18, v18, v70
	v_ldexp_f32 v19, v19, v71
	v_pk_mul_f32 v[20:21], v[20:21], v[24:25]
	v_pk_mul_f32 v[22:23], v[22:23], v[26:27]
	v_pk_fma_f32 v[16:17], v[16:17], s[16:17], v[20:21] op_sel_hi:[1,0,1]
	v_pk_fma_f32 v[18:19], v[18:19], s[16:17], v[22:23] op_sel_hi:[1,0,1]
	v_cvt_pk_bf16_f32 v16, v16, v17
	v_cvt_pk_bf16_f32 v17, v18, v19
	global_store_dwordx2 v[38:39], v[16:17], off offset:1536
	s_waitcnt vmcnt(16)
; __device__ __forceinline__ unsigned cvt_pk_bf16(float lo, float hi) { const bf16x2_t r = __builtin_convertvector((f32x2){lo, hi}, bf16x2_t); return __builtin_bit_cast(unsigned, r); }
; __device__ __forceinline__ f32x4 ld_fx4(const unsigned long long* p) {
;     const long long a = (long long)p[0], b = (long long)p[1], c = (long long)p[2], d = (long long)p[3];
;     return (f32x4){(float)a, (float)b, (float)c, (float)d} * 9.094947017729282e-13f;
; }
; template <bool FINAL>
; __device__ __forceinline__ void norm_phase(const float* X, const float* mod, bf16_t* H, const float* fg, float* OUT, const unsigned long long* acc64 = nullptr, float* modf = nullptr) {
;     ...
;             const float* mb = mod + (r >> 12) * 6144; const unsigned long long* mb64 = acc64 + (r >> 12) * 6144;
; #pragma unroll
;             for (int j = 0; j < 8; ++j) { const f32x4 sh = acc64 ? ld_fx4(mb64 + 4 * (lane + 64 * j)) : *((const f32x4*)mb + lane + 64 * j), sc = acc64 ? ld_fx4(mb64 + DM + 4 * (lane + 64 * j)) : *((const f32x4*)(mb + DM) + lane + 64 * j);
;                 const f32x4 o = v[j] * rstd * (sc + 1.0f) + sh; u32x2 w; w.x = cvt_pk_bf16(o[0], o[1]); w.y = cvt_pk_bf16(o[2], o[3]);
;                 *((u32x2*)(H + (size_t)r * DM) + lane + 64 * j) = w; }
	v_mov_b32_e32 v16, v184
	v_mov_b32_e32 v17, v185
	v_mov_b32_e32 v18, v186
	v_mov_b32_e32 v19, v187
	v_mov_b32_e32 v20, v188
	v_mov_b32_e32 v21, v189
	v_mov_b32_e32 v22, v190
	v_mov_b32_e32 v23, v191
	v_mov_b32_e32 v24, v196
	v_mov_b32_e32 v25, v197
	v_mov_b32_e32 v26, v198
	v_mov_b32_e32 v27, v199
	v_mov_b32_e32 v28, v202
	v_mov_b32_e32 v29, v203
	v_mov_b32_e32 v30, v204
	v_mov_b32_e32 v31, v205
	v_xor_b32_e32 v60, v16, v17
	v_xor_b32_e32 v62, v18, v19
	v_xor_b32_e32 v64, v20, v21
	v_xor_b32_e32 v66, v22, v23
	v_xor_b32_e32 v68, v24, v25
	v_xor_b32_e32 v70, v26, v27
	v_xor_b32_e32 v72, v28, v29
	v_xor_b32_e32 v74, v30, v31
	v_ffbh_i32_e32 v61, v17
	v_ffbh_i32_e32 v63, v19
	v_ffbh_i32_e32 v65, v21
	v_ffbh_i32_e32 v67, v23
	v_ffbh_i32_e32 v69, v25
	v_ffbh_i32_e32 v71, v27
	v_ffbh_i32_e32 v73, v29
	v_ffbh_i32_e32 v75, v31
	v_ashrrev_i32_e32 v60, 31, v60
	v_ashrrev_i32_e32 v62, 31, v62
	v_ashrrev_i32_e32 v64, 31, v64
	v_ashrrev_i32_e32 v66, 31, v66
	v_ashrrev_i32_e32 v68, 31, v68
	v_ashrrev_i32_e32 v70, 31, v70
	v_ashrrev_i32_e32 v72, 31, v72
	v_ashrrev_i32_e32 v74, 31, v74
	v_add_u32_e32 v61, -1, v61
	v_add_u32_e32 v63, -1, v63
	v_add_u32_e32 v65, -1, v65
	v_add_u32_e32 v67, -1, v67
	v_add_u32_e32 v69, -1, v69
	v_add_u32_e32 v71, -1, v71
	v_add_u32_e32 v73, -1, v73
	v_add_u32_e32 v75, -1, v75
	v_add_u32_e32 v60, 32, v60
	v_add_u32_e32 v62, 32, v62
	v_add_u32_e32 v64, 32, v64
	v_add_u32_e32 v66, 32, v66
	v_add_u32_e32 v68, 32, v68
	v_add_u32_e32 v70, 32, v70
	v_add_u32_e32 v72, 32, v72
	v_add_u32_e32 v74, 32, v74
	v_min_u32_e32 v60, v61, v60
	v_min_u32_e32 v61, v63, v62
	v_min_u32_e32 v62, v65, v64
	v_min_u32_e32 v63, v67, v66
	v_min_u32_e32 v64, v69, v68
	v_min_u32_e32 v65, v71, v70
	v_min_u32_e32 v66, v73, v72
	v_min_u32_e32 v67, v75, v74
	v_lshlrev_b64 v[16:17], v60, v[16:17]
	v_lshlrev_b64 v[18:19], v61, v[18:19]
	v_lshlrev_b64 v[20:21], v62, v[20:21]
	v_lshlrev_b64 v[22:23], v63, v[22:23]
	v_lshlrev_b64 v[24:25], v64, v[24:25]
	v_lshlrev_b64 v[26:27], v65, v[26:27]
	v_lshlrev_b64 v[28:29], v66, v[28:29]
	v_lshlrev_b64 v[30:31], v67, v[30:31]
	v_min_u32_e32 v16, 1, v16
	v_min_u32_e32 v18, 1, v18
	v_min_u32_e32 v20, 1, v20
	v_min_u32_e32 v22, 1, v22
	v_min_u32_e32 v24, 1, v24
	v_min_u32_e32 v26, 1, v26
	v_min_u32_e32 v28, 1, v28
	v_min_u32_e32 v30, 1, v30
	v_or_b32_e32 v16, v17, v16
	v_or_b32_e32 v17, v19, v18
	v_or_b32_e32 v18, v21, v20
	v_or_b32_e32 v19, v23, v22
	v_or_b32_e32 v20, v25, v24
	v_or_b32_e32 v21, v27, v26
	v_or_b32_e32 v22, v29, v28
	v_or_b32_e32 v23, v31, v30
	v_cvt_f32_i32_e32 v20, v20
	v_cvt_f32_i32_e32 v21, v21
	v_cvt_f32_i32_e32 v22, v22
	v_cvt_f32_i32_e32 v23, v23
	v_cvt_f32_i32_e32 v16, v16
	v_cvt_f32_i32_e32 v17, v17
	v_cvt_f32_i32_e32 v18, v18
	v_cvt_f32_i32_e32 v19, v19
	v_sub_u32_e32 v64, 32, v64
	v_sub_u32_e32 v65, 32, v65
	v_sub_u32_e32 v66, 32, v66
	v_sub_u32_e32 v67, 32, v67
	v_ldexp_f32 v20, v20, v64
	v_ldexp_f32 v21, v21, v65
	v_ldexp_f32 v22, v22, v66
	v_ldexp_f32 v23, v23, v67
	v_sub_u32_e32 v60, 32, v60
	v_sub_u32_e32 v61, 32, v61
	v_sub_u32_e32 v62, 32, v62
	v_sub_u32_e32 v63, 32, v63
	v_pk_fma_f32 v[20:21], v[20:21], s[16:17], 1.0 op_sel_hi:[1,0,0]
	v_pk_fma_f32 v[22:23], v[22:23], s[16:17], 1.0 op_sel_hi:[1,0,0]
	v_ldexp_f32 v16, v16, v60
	v_ldexp_f32 v17, v17, v61
	v_ldexp_f32 v18, v18, v62
	v_ldexp_f32 v19, v19, v63
	v_pk_mul_f32 v[12:13], v[12:13], v[20:21]
	v_pk_mul_f32 v[14:15], v[14:15], v[22:23]
	v_pk_fma_f32 v[12:13], v[16:17], s[16:17], v[12:13] op_sel_hi:[1,0,1]
	v_pk_fma_f32 v[14:15], v[18:19], s[16:17], v[14:15] op_sel_hi:[1,0,1]
	v_cvt_pk_bf16_f32 v12, v12, v13
	v_cvt_pk_bf16_f32 v13, v14, v15
	global_store_dwordx2 v[38:39], v[12:13], off offset:2048
	s_waitcnt vmcnt(13)
	v_mov_b32_e32 v12, v206
	v_mov_b32_e32 v13, v207
	v_mov_b32_e32 v14, v208
	v_mov_b32_e32 v15, v209
	v_mov_b32_e32 v16, v210
	v_mov_b32_e32 v17, v211
	v_mov_b32_e32 v18, v212
	v_mov_b32_e32 v19, v213
	v_mov_b32_e32 v20, v214
	v_mov_b32_e32 v21, v215
	v_mov_b32_e32 v22, v216
	v_mov_b32_e32 v23, v217
	v_mov_b32_e32 v24, v218
	v_mov_b32_e32 v25, v219
	v_mov_b32_e32 v26, v220
	v_mov_b32_e32 v27, v221
	v_xor_b32_e32 v28, v12, v13
	v_xor_b32_e32 v30, v14, v15
	v_xor_b32_e32 v52, v16, v17
	v_xor_b32_e32 v54, v18, v19
	v_xor_b32_e32 v56, v20, v21
	v_xor_b32_e32 v58, v22, v23
	v_xor_b32_e32 v60, v24, v25
	v_xor_b32_e32 v62, v26, v27
	v_ffbh_i32_e32 v29, v13
	v_ffbh_i32_e32 v31, v15
	v_ffbh_i32_e32 v53, v17
	v_ffbh_i32_e32 v55, v19
	v_ffbh_i32_e32 v57, v21
	v_ffbh_i32_e32 v59, v23
	v_ffbh_i32_e32 v61, v25
	v_ffbh_i32_e32 v63, v27
	v_ashrrev_i32_e32 v28, 31, v28
	v_ashrrev_i32_e32 v30, 31, v30
	v_ashrrev_i32_e32 v52, 31, v52
	v_ashrrev_i32_e32 v54, 31, v54
	v_ashrrev_i32_e32 v56, 31, v56
	v_ashrrev_i32_e32 v58, 31, v58
	v_ashrrev_i32_e32 v60, 31, v60
	v_ashrrev_i32_e32 v62, 31, v62
	v_add_u32_e32 v29, -1, v29
	v_add_u32_e32 v31, -1, v31
	v_add_u32_e32 v53, -1, v53
	v_add_u32_e32 v55, -1, v55
	v_add_u32_e32 v57, -1, v57
	v_add_u32_e32 v59, -1, v59
	v_add_u32_e32 v61, -1, v61
	v_add_u32_e32 v63, -1, v63
	v_add_u32_e32 v28, 32, v28
	v_add_u32_e32 v30, 32, v30
	v_add_u32_e32 v52, 32, v52
	v_add_u32_e32 v54, 32, v54
	v_add_u32_e32 v56, 32, v56
	v_add_u32_e32 v58, 32, v58
	v_add_u32_e32 v60, 32, v60
	v_add_u32_e32 v62, 32, v62
	v_min_u32_e32 v28, v29, v28
	v_min_u32_e32 v29, v31, v30
	v_min_u32_e32 v30, v53, v52
	v_min_u32_e32 v31, v55, v54
	v_min_u32_e32 v52, v57, v56
	v_min_u32_e32 v53, v59, v58
	v_min_u32_e32 v54, v61, v60
	v_min_u32_e32 v55, v63, v62
	v_lshlrev_b64 v[12:13], v28, v[12:13]
	v_lshlrev_b64 v[14:15], v29, v[14:15]
	v_lshlrev_b64 v[16:17], v30, v[16:17]
	v_lshlrev_b64 v[18:19], v31, v[18:19]
	v_lshlrev_b64 v[20:21], v52, v[20:21]
; __device__ __forceinline__ unsigned cvt_pk_bf16(float lo, float hi) { const bf16x2_t r = __builtin_convertvector((f32x2){lo, hi}, bf16x2_t); return __builtin_bit_cast(unsigned, r); }
; __device__ __forceinline__ f32x4 ld_fx4(const unsigned long long* p) {
;     const long long a = (long long)p[0], b = (long long)p[1], c = (long long)p[2], d = (long long)p[3];
;     return (f32x4){(float)a, (float)b, (float)c, (float)d} * 9.094947017729282e-13f;
; }
; template <bool FINAL>
; __device__ __forceinline__ void norm_phase(const float* X, const float* mod, bf16_t* H, const float* fg, float* OUT, const unsigned long long* acc64 = nullptr, float* modf = nullptr) {
;     ...
;             const float* mb = mod + (r >> 12) * 6144; const unsigned long long* mb64 = acc64 + (r >> 12) * 6144;
; #pragma unroll
;             for (int j = 0; j < 8; ++j) { const f32x4 sh = acc64 ? ld_fx4(mb64 + 4 * (lane + 64 * j)) : *((const f32x4*)mb + lane + 64 * j), sc = acc64 ? ld_fx4(mb64 + DM + 4 * (lane + 64 * j)) : *((const f32x4*)(mb + DM) + lane + 64 * j);
;                 const f32x4 o = v[j] * rstd * (sc + 1.0f) + sh; u32x2 w; w.x = cvt_pk_bf16(o[0], o[1]); w.y = cvt_pk_bf16(o[2], o[3]);
;                 *((u32x2*)(H + (size_t)r * DM) + lane + 64 * j) = w; }
	v_lshlrev_b64 v[22:23], v53, v[22:23]
	v_lshlrev_b64 v[24:25], v54, v[24:25]
	v_lshlrev_b64 v[26:27], v55, v[26:27]
	v_min_u32_e32 v12, 1, v12
	v_min_u32_e32 v14, 1, v14
	v_min_u32_e32 v16, 1, v16
	v_min_u32_e32 v18, 1, v18
	v_min_u32_e32 v20, 1, v20
	v_min_u32_e32 v22, 1, v22
	v_min_u32_e32 v24, 1, v24
	v_min_u32_e32 v26, 1, v26
	v_or_b32_e32 v12, v13, v12
	v_or_b32_e32 v13, v15, v14
	v_or_b32_e32 v14, v17, v16
	v_or_b32_e32 v15, v19, v18
	v_or_b32_e32 v16, v21, v20
	v_or_b32_e32 v17, v23, v22
	v_or_b32_e32 v18, v25, v24
	v_or_b32_e32 v19, v27, v26
	v_cvt_f32_i32_e32 v16, v16
	v_cvt_f32_i32_e32 v17, v17
	v_cvt_f32_i32_e32 v18, v18
	v_cvt_f32_i32_e32 v19, v19
	v_cvt_f32_i32_e32 v12, v12
	v_cvt_f32_i32_e32 v13, v13
	v_cvt_f32_i32_e32 v14, v14
	v_cvt_f32_i32_e32 v15, v15
	v_sub_u32_e32 v52, 32, v52
	v_sub_u32_e32 v53, 32, v53
	v_sub_u32_e32 v54, 32, v54
	v_sub_u32_e32 v55, 32, v55
	v_ldexp_f32 v16, v16, v52
	v_ldexp_f32 v17, v17, v53
	v_ldexp_f32 v18, v18, v54
	v_ldexp_f32 v19, v19, v55
	v_sub_u32_e32 v28, 32, v28
	v_sub_u32_e32 v29, 32, v29
	v_sub_u32_e32 v30, 32, v30
	v_sub_u32_e32 v31, 32, v31
	v_pk_fma_f32 v[16:17], v[16:17], s[16:17], 1.0 op_sel_hi:[1,0,0]
	v_pk_fma_f32 v[18:19], v[18:19], s[16:17], 1.0 op_sel_hi:[1,0,0]
	v_ldexp_f32 v12, v12, v28
	v_ldexp_f32 v13, v13, v29
	v_ldexp_f32 v14, v14, v30
	v_ldexp_f32 v15, v15, v31
	v_pk_mul_f32 v[10:11], v[10:11], v[16:17]
	v_pk_mul_f32 v[8:9], v[8:9], v[18:19]
	v_pk_fma_f32 v[10:11], v[12:13], s[16:17], v[10:11] op_sel_hi:[1,0,1]
	v_pk_fma_f32 v[8:9], v[14:15], s[16:17], v[8:9] op_sel_hi:[1,0,1]
	v_cvt_pk_bf16_f32 v10, v10, v11
	v_cvt_pk_bf16_f32 v11, v8, v9
	global_store_dwordx2 v[38:39], v[10:11], off offset:2560
	s_waitcnt vmcnt(10)
	v_mov_b32_e32 v8, v222
	v_mov_b32_e32 v9, v223
	v_mov_b32_e32 v10, v224
	v_mov_b32_e32 v11, v225
	v_mov_b32_e32 v12, v226
	v_mov_b32_e32 v13, v227
	v_mov_b32_e32 v14, v228
	v_mov_b32_e32 v15, v229
	v_mov_b32_e32 v16, v230
	v_mov_b32_e32 v17, v231
	v_mov_b32_e32 v18, v232
	v_mov_b32_e32 v19, v233
	v_mov_b32_e32 v20, v234
	v_mov_b32_e32 v21, v235
	v_mov_b32_e32 v22, v236
	v_mov_b32_e32 v23, v237
	v_xor_b32_e32 v24, v8, v9
	v_xor_b32_e32 v26, v10, v11
	v_xor_b32_e32 v28, v12, v13
	v_xor_b32_e32 v30, v14, v15
	v_xor_b32_e32 v48, v16, v17
	v_xor_b32_e32 v50, v18, v19
	v_xor_b32_e32 v52, v20, v21
	v_xor_b32_e32 v54, v22, v23
	v_ffbh_i32_e32 v25, v9
	v_ffbh_i32_e32 v27, v11
	v_ffbh_i32_e32 v29, v13
	v_ffbh_i32_e32 v31, v15
	v_ffbh_i32_e32 v49, v17
	v_ffbh_i32_e32 v51, v19
	v_ffbh_i32_e32 v53, v21
	v_ffbh_i32_e32 v55, v23
	v_ashrrev_i32_e32 v24, 31, v24
	v_ashrrev_i32_e32 v26, 31, v26
	v_ashrrev_i32_e32 v28, 31, v28
	v_ashrrev_i32_e32 v30, 31, v30
	v_ashrrev_i32_e32 v48, 31, v48
	v_ashrrev_i32_e32 v50, 31, v50
	v_ashrrev_i32_e32 v52, 31, v52
	v_ashrrev_i32_e32 v54, 31, v54
	v_add_u32_e32 v25, -1, v25
	v_add_u32_e32 v27, -1, v27
	v_add_u32_e32 v29, -1, v29
	v_add_u32_e32 v31, -1, v31
	v_add_u32_e32 v49, -1, v49
	v_add_u32_e32 v51, -1, v51
	v_add_u32_e32 v53, -1, v53
	v_add_u32_e32 v55, -1, v55
	v_add_u32_e32 v24, 32, v24
	v_add_u32_e32 v26, 32, v26
	v_add_u32_e32 v28, 32, v28
	v_add_u32_e32 v30, 32, v30
	v_add_u32_e32 v48, 32, v48
	v_add_u32_e32 v50, 32, v50
	v_add_u32_e32 v52, 32, v52
	v_add_u32_e32 v54, 32, v54
	v_min_u32_e32 v24, v25, v24
	v_min_u32_e32 v25, v27, v26
	v_min_u32_e32 v26, v29, v28
	v_min_u32_e32 v27, v31, v30
	v_min_u32_e32 v28, v49, v48
	v_min_u32_e32 v29, v51, v50
	v_min_u32_e32 v30, v53, v52
	v_min_u32_e32 v31, v55, v54
	v_lshlrev_b64 v[8:9], v24, v[8:9]
	v_lshlrev_b64 v[10:11], v25, v[10:11]
	v_lshlrev_b64 v[12:13], v26, v[12:13]
	v_lshlrev_b64 v[14:15], v27, v[14:15]
	v_lshlrev_b64 v[16:17], v28, v[16:17]
	v_lshlrev_b64 v[18:19], v29, v[18:19]
	v_lshlrev_b64 v[20:21], v30, v[20:21]
	v_lshlrev_b64 v[22:23], v31, v[22:23]
	v_min_u32_e32 v8, 1, v8
	v_min_u32_e32 v10, 1, v10
	v_min_u32_e32 v12, 1, v12
	v_min_u32_e32 v14, 1, v14
	v_min_u32_e32 v16, 1, v16
	v_min_u32_e32 v18, 1, v18
	v_min_u32_e32 v20, 1, v20
	v_min_u32_e32 v22, 1, v22
	v_or_b32_e32 v8, v9, v8
	v_or_b32_e32 v9, v11, v10
	v_or_b32_e32 v10, v13, v12
	v_or_b32_e32 v11, v15, v14
	v_or_b32_e32 v12, v17, v16
	v_or_b32_e32 v13, v19, v18
	v_or_b32_e32 v14, v21, v20
	v_or_b32_e32 v15, v23, v22
	v_cvt_f32_i32_e32 v12, v12
	v_cvt_f32_i32_e32 v13, v13
	v_cvt_f32_i32_e32 v14, v14
	v_cvt_f32_i32_e32 v15, v15
	v_cvt_f32_i32_e32 v8, v8
	v_cvt_f32_i32_e32 v9, v9
	v_cvt_f32_i32_e32 v10, v10
	v_cvt_f32_i32_e32 v11, v11
	v_sub_u32_e32 v28, 32, v28
	v_sub_u32_e32 v29, 32, v29
	v_sub_u32_e32 v30, 32, v30
	v_sub_u32_e32 v31, 32, v31
	v_ldexp_f32 v12, v12, v28
	v_ldexp_f32 v13, v13, v29
	v_ldexp_f32 v14, v14, v30
	v_ldexp_f32 v15, v15, v31
	v_sub_u32_e32 v24, 32, v24
	v_sub_u32_e32 v25, 32, v25
	v_sub_u32_e32 v26, 32, v26
	v_sub_u32_e32 v27, 32, v27
	v_pk_fma_f32 v[12:13], v[12:13], s[16:17], 1.0 op_sel_hi:[1,0,0]
	v_pk_fma_f32 v[14:15], v[14:15], s[16:17], 1.0 op_sel_hi:[1,0,0]
	v_ldexp_f32 v8, v8, v24
	v_ldexp_f32 v9, v9, v25
	v_ldexp_f32 v10, v10, v26
	v_ldexp_f32 v11, v11, v27
	v_pk_mul_f32 v[6:7], v[6:7], v[12:13]
	v_pk_mul_f32 v[4:5], v[4:5], v[14:15]
	v_pk_fma_f32 v[6:7], v[8:9], s[16:17], v[6:7] op_sel_hi:[1,0,1]
	v_pk_fma_f32 v[4:5], v[10:11], s[16:17], v[4:5] op_sel_hi:[1,0,1]
	v_cvt_pk_bf16_f32 v6, v6, v7
	v_cvt_pk_bf16_f32 v7, v4, v5
	global_store_dwordx2 v[38:39], v[6:7], off offset:3072
	s_waitcnt vmcnt(7)
; __device__ __forceinline__ unsigned cvt_pk_bf16(float lo, float hi) { const bf16x2_t r = __builtin_convertvector((f32x2){lo, hi}, bf16x2_t); return __builtin_bit_cast(unsigned, r); }
; __device__ __forceinline__ f32x4 ld_fx4(const unsigned long long* p) {
;     const long long a = (long long)p[0], b = (long long)p[1], c = (long long)p[2], d = (long long)p[3];
;     return (f32x4){(float)a, (float)b, (float)c, (float)d} * 9.094947017729282e-13f;
; }
; template <bool FINAL>
; __device__ __forceinline__ void norm_phase(const float* X, const float* mod, bf16_t* H, const float* fg, float* OUT, const unsigned long long* acc64 = nullptr, float* modf = nullptr) {
;     ...
;             const float* mb = mod + (r >> 12) * 6144; const unsigned long long* mb64 = acc64 + (r >> 12) * 6144;
; #pragma unroll
;             for (int j = 0; j < 8; ++j) { const f32x4 sh = acc64 ? ld_fx4(mb64 + 4 * (lane + 64 * j)) : *((const f32x4*)mb + lane + 64 * j), sc = acc64 ? ld_fx4(mb64 + DM + 4 * (lane + 64 * j)) : *((const f32x4*)(mb + DM) + lane + 64 * j);
;                 const f32x4 o = v[j] * rstd * (sc + 1.0f) + sh; u32x2 w; w.x = cvt_pk_bf16(o[0], o[1]); w.y = cvt_pk_bf16(o[2], o[3]);
;                 *((u32x2*)(H + (size_t)r * DM) + lane + 64 * j) = w; }
;         }
;     }
	v_mov_b32_e32 v4, v238
	v_mov_b32_e32 v5, v239
	v_mov_b32_e32 v6, v240
	v_mov_b32_e32 v7, v241
	v_mov_b32_e32 v8, v242
	v_mov_b32_e32 v9, v243
	v_mov_b32_e32 v10, v244
	v_mov_b32_e32 v11, v245
	v_mov_b32_e32 v12, v246
	v_mov_b32_e32 v13, v247
	v_mov_b32_e32 v14, v248
	v_mov_b32_e32 v15, v249
	v_mov_b32_e32 v16, v250
	v_mov_b32_e32 v17, v251
	v_mov_b32_e32 v18, v252
	v_mov_b32_e32 v19, v253
	v_xor_b32_e32 v20, v4, v5
	v_xor_b32_e32 v22, v6, v7
	v_xor_b32_e32 v24, v8, v9
	v_xor_b32_e32 v26, v10, v11
	v_xor_b32_e32 v28, v12, v13
	v_xor_b32_e32 v30, v14, v15
	v_xor_b32_e32 v40, v16, v17
	v_xor_b32_e32 v42, v18, v19
	v_ffbh_i32_e32 v21, v5
	v_ffbh_i32_e32 v23, v7
	v_ffbh_i32_e32 v25, v9
	v_ffbh_i32_e32 v27, v11
	v_ffbh_i32_e32 v29, v13
	v_ffbh_i32_e32 v31, v15
	v_ffbh_i32_e32 v41, v17
	v_ffbh_i32_e32 v43, v19
	v_ashrrev_i32_e32 v20, 31, v20
	v_ashrrev_i32_e32 v22, 31, v22
	v_ashrrev_i32_e32 v24, 31, v24
	v_ashrrev_i32_e32 v26, 31, v26
	v_ashrrev_i32_e32 v28, 31, v28
	v_ashrrev_i32_e32 v30, 31, v30
	v_ashrrev_i32_e32 v40, 31, v40
	v_ashrrev_i32_e32 v42, 31, v42
	v_add_u32_e32 v21, -1, v21
	v_add_u32_e32 v23, -1, v23
	v_add_u32_e32 v25, -1, v25
	v_add_u32_e32 v27, -1, v27
	v_add_u32_e32 v29, -1, v29
	v_add_u32_e32 v31, -1, v31
	v_add_u32_e32 v41, -1, v41
	v_add_u32_e32 v43, -1, v43
	v_add_u32_e32 v20, 32, v20
	v_add_u32_e32 v22, 32, v22
	v_add_u32_e32 v24, 32, v24
	v_add_u32_e32 v26, 32, v26
	v_add_u32_e32 v28, 32, v28
	v_add_u32_e32 v30, 32, v30
	v_add_u32_e32 v40, 32, v40
	v_add_u32_e32 v42, 32, v42
	v_min_u32_e32 v20, v21, v20
	v_min_u32_e32 v21, v23, v22
	v_min_u32_e32 v22, v25, v24
	v_min_u32_e32 v23, v27, v26
	v_min_u32_e32 v24, v29, v28
	v_min_u32_e32 v25, v31, v30
	v_min_u32_e32 v26, v41, v40
	v_min_u32_e32 v27, v43, v42
	v_lshlrev_b64 v[4:5], v20, v[4:5]
	v_lshlrev_b64 v[6:7], v21, v[6:7]
	v_lshlrev_b64 v[8:9], v22, v[8:9]
	v_lshlrev_b64 v[10:11], v23, v[10:11]
	v_lshlrev_b64 v[12:13], v24, v[12:13]
	v_lshlrev_b64 v[14:15], v25, v[14:15]
	v_lshlrev_b64 v[16:17], v26, v[16:17]
	v_lshlrev_b64 v[18:19], v27, v[18:19]
	v_min_u32_e32 v4, 1, v4
	v_min_u32_e32 v6, 1, v6
	v_min_u32_e32 v8, 1, v8
	v_min_u32_e32 v10, 1, v10
	v_min_u32_e32 v12, 1, v12
	v_min_u32_e32 v14, 1, v14
	v_min_u32_e32 v16, 1, v16
	v_min_u32_e32 v18, 1, v18
	v_or_b32_e32 v4, v5, v4
	v_or_b32_e32 v5, v7, v6
	v_or_b32_e32 v6, v9, v8
	v_or_b32_e32 v7, v11, v10
	v_or_b32_e32 v8, v13, v12
	v_or_b32_e32 v9, v15, v14
	v_or_b32_e32 v10, v17, v16
	v_or_b32_e32 v11, v19, v18
	v_cvt_f32_i32_e32 v8, v8
	v_cvt_f32_i32_e32 v9, v9
	v_cvt_f32_i32_e32 v10, v10
	v_cvt_f32_i32_e32 v11, v11
	v_cvt_f32_i32_e32 v4, v4
	v_cvt_f32_i32_e32 v5, v5
	v_cvt_f32_i32_e32 v6, v6
	v_cvt_f32_i32_e32 v7, v7
	v_sub_u32_e32 v24, 32, v24
	v_sub_u32_e32 v25, 32, v25
	v_sub_u32_e32 v26, 32, v26
	v_sub_u32_e32 v27, 32, v27
	v_ldexp_f32 v8, v8, v24
	v_ldexp_f32 v9, v9, v25
	v_ldexp_f32 v10, v10, v26
	v_ldexp_f32 v11, v11, v27
	v_sub_u32_e32 v20, 32, v20
	v_sub_u32_e32 v21, 32, v21
	v_sub_u32_e32 v22, 32, v22
	v_sub_u32_e32 v23, 32, v23
	v_pk_fma_f32 v[8:9], v[8:9], s[16:17], 1.0 op_sel_hi:[1,0,0]
	v_pk_fma_f32 v[10:11], v[10:11], s[16:17], 1.0 op_sel_hi:[1,0,0]
	v_ldexp_f32 v4, v4, v20
	v_ldexp_f32 v5, v5, v21
	v_ldexp_f32 v6, v6, v22
	v_ldexp_f32 v7, v7, v23
	v_pk_mul_f32 v[2:3], v[2:3], v[8:9]
	v_pk_mul_f32 v[0:1], v[0:1], v[10:11]
	v_pk_fma_f32 v[2:3], v[4:5], s[16:17], v[2:3] op_sel_hi:[1,0,1]
	v_pk_fma_f32 v[0:1], v[6:7], s[16:17], v[0:1] op_sel_hi:[1,0,1]
	v_cvt_pk_bf16_f32 v2, v2, v3
	v_cvt_pk_bf16_f32 v3, v0, v1
	global_store_dwordx2 v[38:39], v[2:3], off offset:3584
	v_lshl_add_u64 v[38:39], v[38:39], 0, s[10:11]
	s_andn2_b64 exec, exec, s[12:13]
	s_cbranch_execnz .LBB0_121

; __device__ __forceinline__ unsigned cvt_pk_bf16(float lo, float hi) { const bf16x2_t r = __builtin_convertvector((f32x2){lo, hi}, bf16x2_t); return __builtin_bit_cast(unsigned, r); }
; __device__ __forceinline__ float bf_lo(unsigned w) { return __uint_as_float(w << 16); }
; __device__ __forceinline__ float bf_hi(unsigned w) { return __uint_as_float(w & 0xffff0000u); }
; __device__ __forceinline__ void scan2_phase(const unsigned* AU, const float* PA, const float* PH, const bf16_t* GB, bf16_t* AB) {
;     ...
; #pragma unroll 16
;         for (int t = 0; t < SCL; ++t) { const u32x2 w = *(const u32x2*)(AU + base + (size_t)t * DM);
;             const unsigned g = *(const unsigned*)(GB + base + (size_t)t * DM);
;             h0 = (1.0f - bf_lo(w.x)) * h0 + bf_hi(w.x); h1 = (1.0f - bf_lo(w.y)) * h1 + bf_hi(w.y);
;             *(unsigned*)(AB + base + (size_t)t * DM) = cvt_pk_bf16(h0 * bf_lo(g), h1 * bf_hi(g)); }
.Lsc2_top:
	global_load_dwordx2 v[32:33], v4, s[98:99] nt
	global_load_dword v64, v2, s[100:101] nt
	s_add_u32 s98, s98, 0x2000
	s_addc_u32 s99, s99, 0
	s_add_u32 s100, s100, 0x1000
	s_addc_u32 s101, s101, 0
	global_load_dwordx2 v[34:35], v4, s[98:99] nt
	global_load_dword v65, v2, s[100:101] nt
	s_add_u32 s98, s98, 0x2000
	s_addc_u32 s99, s99, 0
	s_add_u32 s100, s100, 0x1000
	s_addc_u32 s101, s101, 0
	global_load_dwordx2 v[36:37], v4, s[98:99] nt
	global_load_dword v66, v2, s[100:101] nt
	s_add_u32 s98, s98, 0x2000
	s_addc_u32 s99, s99, 0
	s_add_u32 s100, s100, 0x1000
	s_addc_u32 s101, s101, 0
	global_load_dwordx2 v[38:39], v4, s[98:99] nt
	global_load_dword v67, v2, s[100:101] nt
	s_add_u32 s98, s98, 0x2000
	s_addc_u32 s99, s99, 0
	s_add_u32 s100, s100, 0x1000
	s_addc_u32 s101, s101, 0
	global_load_dwordx2 v[40:41], v4, s[98:99] nt
	global_load_dword v68, v2, s[100:101] nt
	s_add_u32 s98, s98, 0x2000
	s_addc_u32 s99, s99, 0
	s_add_u32 s100, s100, 0x1000
	s_addc_u32 s101, s101, 0
	global_load_dwordx2 v[42:43], v4, s[98:99] nt
	global_load_dword v69, v2, s[100:101] nt
	s_add_u32 s98, s98, 0x2000
	s_addc_u32 s99, s99, 0
	s_add_u32 s100, s100, 0x1000
	s_addc_u32 s101, s101, 0
	global_load_dwordx2 v[44:45], v4, s[98:99] nt
	global_load_dword v70, v2, s[100:101] nt
	s_add_u32 s98, s98, 0x2000
	s_addc_u32 s99, s99, 0
	s_add_u32 s100, s100, 0x1000
	s_addc_u32 s101, s101, 0
	global_load_dwordx2 v[46:47], v4, s[98:99] nt
	global_load_dword v71, v2, s[100:101] nt
	s_add_u32 s98, s98, 0x2000
	s_addc_u32 s99, s99, 0
	s_add_u32 s100, s100, 0x1000
	s_addc_u32 s101, s101, 0
	global_load_dwordx2 v[48:49], v4, s[98:99] nt
	global_load_dword v72, v2, s[100:101] nt
	s_add_u32 s98, s98, 0x2000
	s_addc_u32 s99, s99, 0
	s_add_u32 s100, s100, 0x1000
	s_addc_u32 s101, s101, 0
	global_load_dwordx2 v[50:51], v4, s[98:99] nt
	global_load_dword v73, v2, s[100:101] nt
	s_add_u32 s98, s98, 0x2000
	s_addc_u32 s99, s99, 0
	s_add_u32 s100, s100, 0x1000
	s_addc_u32 s101, s101, 0
	global_load_dwordx2 v[52:53], v4, s[98:99] nt
	global_load_dword v74, v2, s[100:101] nt
	s_add_u32 s98, s98, 0x2000
	s_addc_u32 s99, s99, 0
	s_add_u32 s100, s100, 0x1000
	s_addc_u32 s101, s101, 0
	global_load_dwordx2 v[54:55], v4, s[98:99] nt
	global_load_dword v75, v2, s[100:101] nt
	s_add_u32 s98, s98, 0x2000
	s_addc_u32 s99, s99, 0
	s_add_u32 s100, s100, 0x1000
	s_addc_u32 s101, s101, 0
	global_load_dwordx2 v[56:57], v4, s[98:99] nt
	global_load_dword v76, v2, s[100:101] nt
	s_add_u32 s98, s98, 0x2000
	s_addc_u32 s99, s99, 0
	s_add_u32 s100, s100, 0x1000
	s_addc_u32 s101, s101, 0
	global_load_dwordx2 v[58:59], v4, s[98:99] nt
	global_load_dword v77, v2, s[100:101] nt
	s_add_u32 s98, s98, 0x2000
	s_addc_u32 s99, s99, 0
	s_add_u32 s100, s100, 0x1000
	s_addc_u32 s101, s101, 0
	global_load_dwordx2 v[60:61], v4, s[98:99] nt
	global_load_dword v78, v2, s[100:101] nt
	s_add_u32 s98, s98, 0x2000
	s_addc_u32 s99, s99, 0
	s_add_u32 s100, s100, 0x1000
	s_addc_u32 s101, s101, 0
	global_load_dwordx2 v[62:63], v4, s[98:99] nt
	global_load_dword v79, v2, s[100:101] nt
	s_add_u32 s98, s98, 0x2000
	s_addc_u32 s99, s99, 0
	s_add_u32 s100, s100, 0x1000
	s_addc_u32 s101, s101, 0
	s_waitcnt vmcnt(30)
	v_lshlrev_b32_e32 v17, 16, v33
	v_lshlrev_b32_e32 v16, 16, v32
	v_pk_add_f32 v[16:17], v[16:17], 1.0 op_sel_hi:[1,0] neg_lo:[1,0] neg_hi:[1,0]
	v_and_b32_e32 v19, 0xffff0000, v33
	v_and_b32_e32 v18, 0xffff0000, v32
	v_pk_fma_f32 v[8:9], v[8:9], v[16:17], v[18:19]
	v_lshlrev_b32_e32 v20, 16, v64
	v_and_b32_e32 v21, 0xffff0000, v64
	v_pk_mul_f32 v[20:21], v[8:9], v[20:21]
	s_nop 0
	v_cvt_pk_bf16_f32 v64, v20, v21
	global_store_dword v2, v64, s[28:29]
	s_add_u32 s28, s28, 0x1000
	s_addc_u32 s29, s29, 0
	s_waitcnt vmcnt(29)
	v_lshlrev_b32_e32 v17, 16, v35
	v_lshlrev_b32_e32 v16, 16, v34
	v_pk_add_f32 v[16:17], v[16:17], 1.0 op_sel_hi:[1,0] neg_lo:[1,0] neg_hi:[1,0]
	v_and_b32_e32 v19, 0xffff0000, v35
	v_and_b32_e32 v18, 0xffff0000, v34
	v_pk_fma_f32 v[8:9], v[8:9], v[16:17], v[18:19]
	v_lshlrev_b32_e32 v20, 16, v65
	v_and_b32_e32 v21, 0xffff0000, v65
	v_pk_mul_f32 v[20:21], v[8:9], v[20:21]
	s_nop 0
	v_cvt_pk_bf16_f32 v65, v20, v21
	global_store_dword v2, v65, s[28:29]
	s_add_u32 s28, s28, 0x1000
	s_addc_u32 s29, s29, 0
	s_waitcnt vmcnt(28)
	v_lshlrev_b32_e32 v17, 16, v37
	v_lshlrev_b32_e32 v16, 16, v36
	v_pk_add_f32 v[16:17], v[16:17], 1.0 op_sel_hi:[1,0] neg_lo:[1,0] neg_hi:[1,0]
	v_and_b32_e32 v19, 0xffff0000, v37
	v_and_b32_e32 v18, 0xffff0000, v36
	v_pk_fma_f32 v[8:9], v[8:9], v[16:17], v[18:19]
	v_lshlrev_b32_e32 v20, 16, v66
	v_and_b32_e32 v21, 0xffff0000, v66
	v_pk_mul_f32 v[20:21], v[8:9], v[20:21]
	s_nop 0
	v_cvt_pk_bf16_f32 v66, v20, v21
	global_store_dword v2, v66, s[28:29]
	s_add_u32 s28, s28, 0x1000
	s_addc_u32 s29, s29, 0
	s_waitcnt vmcnt(27)
	v_lshlrev_b32_e32 v17, 16, v39
	v_lshlrev_b32_e32 v16, 16, v38
	v_pk_add_f32 v[16:17], v[16:17], 1.0 op_sel_hi:[1,0] neg_lo:[1,0] neg_hi:[1,0]
	v_and_b32_e32 v19, 0xffff0000, v39
	v_and_b32_e32 v18, 0xffff0000, v38
	v_pk_fma_f32 v[8:9], v[8:9], v[16:17], v[18:19]
	v_lshlrev_b32_e32 v20, 16, v67
	v_and_b32_e32 v21, 0xffff0000, v67
	v_pk_mul_f32 v[20:21], v[8:9], v[20:21]
	s_nop 0
	v_cvt_pk_bf16_f32 v67, v20, v21
	global_store_dword v2, v67, s[28:29]
	s_add_u32 s28, s28, 0x1000
	s_addc_u32 s29, s29, 0
	s_waitcnt vmcnt(26)
	v_lshlrev_b32_e32 v17, 16, v41
	v_lshlrev_b32_e32 v16, 16, v40
	v_pk_add_f32 v[16:17], v[16:17], 1.0 op_sel_hi:[1,0] neg_lo:[1,0] neg_hi:[1,0]
	v_and_b32_e32 v19, 0xffff0000, v41
	v_and_b32_e32 v18, 0xffff0000, v40
	v_pk_fma_f32 v[8:9], v[8:9], v[16:17], v[18:19]
	v_lshlrev_b32_e32 v20, 16, v68
	v_and_b32_e32 v21, 0xffff0000, v68
	v_pk_mul_f32 v[20:21], v[8:9], v[20:21]
	s_nop 0
	v_cvt_pk_bf16_f32 v68, v20, v21
	global_store_dword v2, v68, s[28:29]
	s_add_u32 s28, s28, 0x1000
	s_addc_u32 s29, s29, 0
	s_waitcnt vmcnt(25)
; __device__ __forceinline__ unsigned cvt_pk_bf16(float lo, float hi) { const bf16x2_t r = __builtin_convertvector((f32x2){lo, hi}, bf16x2_t); return __builtin_bit_cast(unsigned, r); }
; __device__ __forceinline__ float bf_lo(unsigned w) { return __uint_as_float(w << 16); }
; __device__ __forceinline__ float bf_hi(unsigned w) { return __uint_as_float(w & 0xffff0000u); }
; __device__ __forceinline__ void scan2_phase(const unsigned* AU, const float* PA, const float* PH, const bf16_t* GB, bf16_t* AB) {
;     ...
; #pragma unroll 16
;         for (int t = 0; t < SCL; ++t) { const u32x2 w = *(const u32x2*)(AU + base + (size_t)t * DM);
;             const unsigned g = *(const unsigned*)(GB + base + (size_t)t * DM);
;             h0 = (1.0f - bf_lo(w.x)) * h0 + bf_hi(w.x); h1 = (1.0f - bf_lo(w.y)) * h1 + bf_hi(w.y);
;             *(unsigned*)(AB + base + (size_t)t * DM) = cvt_pk_bf16(h0 * bf_lo(g), h1 * bf_hi(g)); }
;     }
	v_lshlrev_b32_e32 v17, 16, v43
	v_lshlrev_b32_e32 v16, 16, v42
	v_pk_add_f32 v[16:17], v[16:17], 1.0 op_sel_hi:[1,0] neg_lo:[1,0] neg_hi:[1,0]
	v_and_b32_e32 v19, 0xffff0000, v43
	v_and_b32_e32 v18, 0xffff0000, v42
	v_pk_fma_f32 v[8:9], v[8:9], v[16:17], v[18:19]
	v_lshlrev_b32_e32 v20, 16, v69
	v_and_b32_e32 v21, 0xffff0000, v69
	v_pk_mul_f32 v[20:21], v[8:9], v[20:21]
	s_nop 0
	v_cvt_pk_bf16_f32 v69, v20, v21
	global_store_dword v2, v69, s[28:29]
	s_add_u32 s28, s28, 0x1000
	s_addc_u32 s29, s29, 0
	s_waitcnt vmcnt(24)
	v_lshlrev_b32_e32 v17, 16, v45
	v_lshlrev_b32_e32 v16, 16, v44
	v_pk_add_f32 v[16:17], v[16:17], 1.0 op_sel_hi:[1,0] neg_lo:[1,0] neg_hi:[1,0]
	v_and_b32_e32 v19, 0xffff0000, v45
	v_and_b32_e32 v18, 0xffff0000, v44
	v_pk_fma_f32 v[8:9], v[8:9], v[16:17], v[18:19]
	v_lshlrev_b32_e32 v20, 16, v70
	v_and_b32_e32 v21, 0xffff0000, v70
	v_pk_mul_f32 v[20:21], v[8:9], v[20:21]
	s_nop 0
	v_cvt_pk_bf16_f32 v70, v20, v21
	global_store_dword v2, v70, s[28:29]
	s_add_u32 s28, s28, 0x1000
	s_addc_u32 s29, s29, 0
	s_waitcnt vmcnt(23)
	v_lshlrev_b32_e32 v17, 16, v47
	v_lshlrev_b32_e32 v16, 16, v46
	v_pk_add_f32 v[16:17], v[16:17], 1.0 op_sel_hi:[1,0] neg_lo:[1,0] neg_hi:[1,0]
	v_and_b32_e32 v19, 0xffff0000, v47
	v_and_b32_e32 v18, 0xffff0000, v46
	v_pk_fma_f32 v[8:9], v[8:9], v[16:17], v[18:19]
	v_lshlrev_b32_e32 v20, 16, v71
	v_and_b32_e32 v21, 0xffff0000, v71
	v_pk_mul_f32 v[20:21], v[8:9], v[20:21]
	s_nop 0
	v_cvt_pk_bf16_f32 v71, v20, v21
	global_store_dword v2, v71, s[28:29]
	s_add_u32 s28, s28, 0x1000
	s_addc_u32 s29, s29, 0
	s_waitcnt vmcnt(22)
	v_lshlrev_b32_e32 v17, 16, v49
	v_lshlrev_b32_e32 v16, 16, v48
	v_pk_add_f32 v[16:17], v[16:17], 1.0 op_sel_hi:[1,0] neg_lo:[1,0] neg_hi:[1,0]
	v_and_b32_e32 v19, 0xffff0000, v49
	v_and_b32_e32 v18, 0xffff0000, v48
	v_pk_fma_f32 v[8:9], v[8:9], v[16:17], v[18:19]
	v_lshlrev_b32_e32 v20, 16, v72
	v_and_b32_e32 v21, 0xffff0000, v72
	v_pk_mul_f32 v[20:21], v[8:9], v[20:21]
	s_nop 0
	v_cvt_pk_bf16_f32 v72, v20, v21
	global_store_dword v2, v72, s[28:29]
	s_add_u32 s28, s28, 0x1000
	s_addc_u32 s29, s29, 0
	s_waitcnt vmcnt(21)
	v_lshlrev_b32_e32 v17, 16, v51
	v_lshlrev_b32_e32 v16, 16, v50
	v_pk_add_f32 v[16:17], v[16:17], 1.0 op_sel_hi:[1,0] neg_lo:[1,0] neg_hi:[1,0]
	v_and_b32_e32 v19, 0xffff0000, v51
	v_and_b32_e32 v18, 0xffff0000, v50
	v_pk_fma_f32 v[8:9], v[8:9], v[16:17], v[18:19]
	v_lshlrev_b32_e32 v20, 16, v73
	v_and_b32_e32 v21, 0xffff0000, v73
	v_pk_mul_f32 v[20:21], v[8:9], v[20:21]
	s_nop 0
	v_cvt_pk_bf16_f32 v73, v20, v21
	global_store_dword v2, v73, s[28:29]
	s_add_u32 s28, s28, 0x1000
	s_addc_u32 s29, s29, 0
	s_waitcnt vmcnt(20)
	v_lshlrev_b32_e32 v17, 16, v53
	v_lshlrev_b32_e32 v16, 16, v52
	v_pk_add_f32 v[16:17], v[16:17], 1.0 op_sel_hi:[1,0] neg_lo:[1,0] neg_hi:[1,0]
	v_and_b32_e32 v19, 0xffff0000, v53
	v_and_b32_e32 v18, 0xffff0000, v52
	v_pk_fma_f32 v[8:9], v[8:9], v[16:17], v[18:19]
	v_lshlrev_b32_e32 v20, 16, v74
	v_and_b32_e32 v21, 0xffff0000, v74
	v_pk_mul_f32 v[20:21], v[8:9], v[20:21]
	s_nop 0
	v_cvt_pk_bf16_f32 v74, v20, v21
	global_store_dword v2, v74, s[28:29]
	s_add_u32 s28, s28, 0x1000
	s_addc_u32 s29, s29, 0
	s_waitcnt vmcnt(19)
	v_lshlrev_b32_e32 v17, 16, v55
	v_lshlrev_b32_e32 v16, 16, v54
	v_pk_add_f32 v[16:17], v[16:17], 1.0 op_sel_hi:[1,0] neg_lo:[1,0] neg_hi:[1,0]
	v_and_b32_e32 v19, 0xffff0000, v55
	v_and_b32_e32 v18, 0xffff0000, v54
	v_pk_fma_f32 v[8:9], v[8:9], v[16:17], v[18:19]
	v_lshlrev_b32_e32 v20, 16, v75
	v_and_b32_e32 v21, 0xffff0000, v75
	v_pk_mul_f32 v[20:21], v[8:9], v[20:21]
	s_nop 0
	v_cvt_pk_bf16_f32 v75, v20, v21
	global_store_dword v2, v75, s[28:29]
	s_add_u32 s28, s28, 0x1000
	s_addc_u32 s29, s29, 0
	s_waitcnt vmcnt(18)
	v_lshlrev_b32_e32 v17, 16, v57
	v_lshlrev_b32_e32 v16, 16, v56
	v_pk_add_f32 v[16:17], v[16:17], 1.0 op_sel_hi:[1,0] neg_lo:[1,0] neg_hi:[1,0]
	v_and_b32_e32 v19, 0xffff0000, v57
	v_and_b32_e32 v18, 0xffff0000, v56
	v_pk_fma_f32 v[8:9], v[8:9], v[16:17], v[18:19]
	v_lshlrev_b32_e32 v20, 16, v76
	v_and_b32_e32 v21, 0xffff0000, v76
	v_pk_mul_f32 v[20:21], v[8:9], v[20:21]
	s_nop 0
	v_cvt_pk_bf16_f32 v76, v20, v21
	global_store_dword v2, v76, s[28:29]
	s_add_u32 s28, s28, 0x1000
	s_addc_u32 s29, s29, 0
	s_waitcnt vmcnt(17)
	v_lshlrev_b32_e32 v17, 16, v59
	v_lshlrev_b32_e32 v16, 16, v58
	v_pk_add_f32 v[16:17], v[16:17], 1.0 op_sel_hi:[1,0] neg_lo:[1,0] neg_hi:[1,0]
	v_and_b32_e32 v19, 0xffff0000, v59
	v_and_b32_e32 v18, 0xffff0000, v58
	v_pk_fma_f32 v[8:9], v[8:9], v[16:17], v[18:19]
	v_lshlrev_b32_e32 v20, 16, v77
	v_and_b32_e32 v21, 0xffff0000, v77
	v_pk_mul_f32 v[20:21], v[8:9], v[20:21]
	s_nop 0
	v_cvt_pk_bf16_f32 v77, v20, v21
	global_store_dword v2, v77, s[28:29]
	s_add_u32 s28, s28, 0x1000
	s_addc_u32 s29, s29, 0
	s_waitcnt vmcnt(16)
	v_lshlrev_b32_e32 v17, 16, v61
	v_lshlrev_b32_e32 v16, 16, v60
	v_pk_add_f32 v[16:17], v[16:17], 1.0 op_sel_hi:[1,0] neg_lo:[1,0] neg_hi:[1,0]
	v_and_b32_e32 v19, 0xffff0000, v61
	v_and_b32_e32 v18, 0xffff0000, v60
	v_pk_fma_f32 v[8:9], v[8:9], v[16:17], v[18:19]
	v_lshlrev_b32_e32 v20, 16, v78
	v_and_b32_e32 v21, 0xffff0000, v78
	v_pk_mul_f32 v[20:21], v[8:9], v[20:21]
	s_nop 0
	v_cvt_pk_bf16_f32 v78, v20, v21
	global_store_dword v2, v78, s[28:29]
	s_add_u32 s28, s28, 0x1000
	s_addc_u32 s29, s29, 0
	s_waitcnt vmcnt(15)
	v_lshlrev_b32_e32 v17, 16, v63
	v_lshlrev_b32_e32 v16, 16, v62
	v_pk_add_f32 v[16:17], v[16:17], 1.0 op_sel_hi:[1,0] neg_lo:[1,0] neg_hi:[1,0]
	v_and_b32_e32 v19, 0xffff0000, v63
	v_and_b32_e32 v18, 0xffff0000, v62
	v_pk_fma_f32 v[8:9], v[8:9], v[16:17], v[18:19]
	v_lshlrev_b32_e32 v20, 16, v79
	v_and_b32_e32 v21, 0xffff0000, v79
	v_pk_mul_f32 v[20:21], v[8:9], v[20:21]
	s_nop 0
	v_cvt_pk_bf16_f32 v79, v20, v21
	global_store_dword v2, v79, s[28:29]
	s_add_u32 s28, s28, 0x1000
	s_addc_u32 s29, s29, 0
	s_add_i32 s44, s44, -1
	s_cmp_eq_u32 s44, 0
	s_cbranch_scc0 .Lsc2_top
	v_add_u32_e32 v12, s33, v12
	v_cmp_lt_i32_e32 vcc, s69, v12
	s_or_b64 s[4:5], vcc, s[4:5]
	v_add_u32_e32 v13, s48, v13
	s_andn2_b64 exec, exec, s[4:5]
	s_cbranch_execnz .LBB0_1016
